# P11 GEMM K-loop prefetches residual tile rows (global_load to dummy regs, 1 row per super-phase), vmcnt 8->9
# baseline (speedup 1.0000x reference)
; #define PG8_WAIT_V(n) asm volatile("s_waitcnt vmcnt(" #n ")" ::: "memory")
; #define PG8_BAR __builtin_amdgcn_s_barrier()
; template <class Epi, class Sched, bool ALIGN_EPI = false, bool SP2 = false>
; __device__ __forceinline__ void gemm_phase(PG8_LAS unsigned char* lds, const Gemm g, const Sched& S, const Epi& E) {
;     int tid = threadIdx.x; asm volatile("" : "+v"(tid)); const int wid = __builtin_amdgcn_readfirstlane(tid >> 6), lane = tid & 63, wr = wid >> 2, wc = wid & 3, fr = lane & 15, fq = lane >> 4;
;     const int K = g.K, nt = K / BK;
;     unsigned voffA[2], voffB[2];
; #pragma unroll
;     for (int i = 0; i < 2; ++i) { int R, C; stage_rc(tid * 16 + i * 8192, R, C); const int Rb = Epi::PERM ? ((R & ~31) + perm32(R & 31)) : R;
;         voffA[i] = (unsigned)(R * K + C) * 2u; voffB[i] = (unsigned)(Rb * K + C) * 2u; }
;     const size_t kstep = (size_t)(BK * 2);
;     const size_t hstep = (size_t)HALF * K * 2;
;     const size_t tstep = 2 * hstep;
;     const unsigned ldsw = (unsigned)wid * 1024u;
;     const int aoff = lds_byte(wr * 64 + fr, fq * 8), boff = lds_byte(wc * 32 + fr, fq * 8);
;     ...
;     Unit cur, nxt; int ui = 0;
;     if (!S.next(0, cur)) return;
;     f32x4 acc[2][2][4][2];
; #pragma unroll
;     for (int a = 0; a < 2; ++a)
; #pragma unroll
;         for (int b = 0; b < 2; ++b)
; #pragma unroll
;             for (int m = 0; m < 4; ++m)
; #pragma unroll
;                 for (int n = 0; n < 2; ++n) acc[a][b][m][n] = (f32x4){0.f, 0.f, 0.f, 0.f};
;     bf16x8 At[4][2], B0[2][2], B1[2][2];
;     const char* cA = (const char*)g.A + (size_t)cur.pm * tstep; const char* cB = (const char*)g.Bt + (size_t)cur.pn * tstep;
;     S.a_ready(cur);
;     if constexpr (SP2) {
;         PG8_STAGE(PG8_SB(0, 0), cB, voffB); PG8_STAGE(PG8_SB(0, 1), cB + hstep, voffB); PG8_STAGE(PG8_SA(0, 0), cA, voffA); PG8_STAGE(PG8_SA(0, 1), cA + hstep, voffA);
;         if (wr == 1) PG8_BAR;
;         PG8_WAIT_V(2); PG8_BAR;
;         PG8_STAGE(PG8_SB(1, 0), cB + kstep, voffB); PG8_STAGE(PG8_SA(1, 0), cA + kstep, voffA); PG8_STAGE(PG8_SB(1, 1), cB + hstep + kstep, voffB);
;         PG8_WAIT_V(6); PG8_BAR;
;     } else {
;         PG8_STAGE(PG8_SB(0, 0), cB, voffB); PG8_STAGE(PG8_SA(0, 0), cA, voffA); PG8_STAGE(PG8_SB(0, 1), cB + hstep, voffB); PG8_STAGE(PG8_SA(0, 1), cA + hstep, voffA);
;         if (wr == 1) PG8_BAR;
;         PG8_WAIT_V(4); PG8_BAR;
.LBB0_984:
	v_and_b32_e32 v250, 63, v216
	v_lshlrev_b32_e32 v250, 4, v250
	v_ashrrev_i32_e32 v1, 31, v216
	v_lshrrev_b32_e32 v1, 26, v1
	v_add_u32_e32 v1, v216, v1
	v_ashrrev_i32_e32 v8, 6, v1
	v_bfe_i32 v1, v216, 27, 1
	v_lshlrev_b32_e32 v0, 4, v216
	v_lshrrev_b32_e32 v1, 22, v1
	v_add_u32_e32 v1, v0, v1
	v_and_b32_e32 v1, 0xfffffc00, v1
	v_sub_u32_e32 v1, v0, v1
	v_lshrrev_b32_e32 v2, 4, v1
	v_bitop3_b32 v1, v2, v1, 32 bitop3:0x6c
	v_ashrrev_i32_e32 v3, 31, v1
	v_lshrrev_b32_e32 v3, 26, v3
	v_add_u32_e32 v3, v1, v3
	v_lshlrev_b32_e32 v2, 3, v8
	v_ashrrev_i32_e32 v9, 6, v3
	v_and_b32_e32 v3, 0xc0, v3
	v_and_b32_e32 v2, -16, v2
	v_sub_u32_e32 v1, v1, v3
	v_mov_b32_e32 v3, 1
	v_add_u32_e32 v2, v9, v2
	v_ashrrev_i16_sdwa v1, v3, sext(v1) dst_sel:DWORD dst_unused:UNUSED_PAD src0_sel:DWORD src1_sel:BYTE_0
	v_lshlrev_b32_e32 v4, 5, v8
	v_bfe_i32 v10, v1, 0, 16
	v_lshlrev_b32_e32 v1, 1, v2
	v_lshrrev_b32_e32 v5, 2, v2
	v_and_b32_e32 v6, 3, v9
	s_mov_b32 s0, 0x1fffe0
	v_and_b32_e32 v4, 32, v4
	v_and_b32_e32 v1, 24, v1
	v_and_b32_e32 v5, 4, v5
	v_and_or_b32 v6, v2, s0, v6
	v_or3_b32 v1, v6, v5, v1
	v_add_lshl_u32 v4, v4, v10, 1
	v_add_u32_e32 v0, 0x2000, v0
	v_lshl_add_u32 v146, v1, 11, v4
	v_ashrrev_i32_e32 v1, 31, v0
	v_lshrrev_b32_e32 v1, 22, v1
	v_add_u32_e32 v1, v0, v1
	v_ashrrev_i32_e32 v11, 10, v1
	v_mul_i32_i24_e32 v1, 0x400, v11
	v_sub_u32_e32 v0, v0, v1
	v_lshrrev_b32_e32 v1, 4, v0
	v_bitop3_b32 v0, v1, v0, 32 bitop3:0x6c
	v_lshl_add_u32 v144, v2, 11, v4
	v_ashrrev_i32_e32 v2, 31, v0
	v_lshrrev_b32_e32 v2, 26, v2
	v_add_u32_e32 v2, v0, v2
	v_lshlrev_b32_e32 v1, 3, v11
	v_ashrrev_i32_e32 v12, 6, v2
	v_and_b32_e32 v2, 0xc0, v2
	v_and_b32_e32 v1, -16, v1
	v_sub_u32_e32 v0, v0, v2
	v_add_u32_e32 v1, v12, v1
	v_ashrrev_i16_sdwa v0, v3, sext(v0) dst_sel:DWORD dst_unused:UNUSED_PAD src0_sel:DWORD src1_sel:BYTE_0
	v_and_b32_e32 v3, 3, v12
	v_and_or_b32 v3, v1, s0, v3
	s_add_i32 s0, s4, s31
	s_ashr_i32 s4, s0, 31
	s_lshr_b32 s4, s4, 27
	s_add_i32 s4, s0, s4
	s_ashr_i32 s5, s4, 5
	s_and_b32 s4, s4, 0xffe0
	s_sub_i32 s4, s0, s4
	s_bfe_i32 s0, s4, 0x80000
	s_bfe_u32 s0, s0, 0x3000c
	s_add_i32 s16, s4, s0
	s_bfe_i32 s0, s16, 0x80000
	s_and_b32 s16, s16, 0xf8
	s_sub_i32 s4, s4, s16
	s_lshl_b32 s5, s5, 3
	s_sext_i32_i16 s0, s0
	s_sext_i32_i8 s4, s4
	s_ashr_i32 s1, s14, 8
	s_lshr_b32 s0, s0, 3
	s_add_i32 s34, s5, s4
	s_ashr_i32 s15, s14, 6
	s_lshl_b32 s98, s34, 8
	s_lshl_b32 s99, s15, 5
	s_add_i32 s98, s98, s99
	s_lshl_b32 s98, s98, 12
	s_lshl_b32 s99, s0, 10
	s_add_u32 s98, s98, s99
	s_add_u32 s98, s8, s98
	s_addc_u32 s99, s9, 0
	s_ashr_i32 s35, s34, 31
	s_bfe_i64 s[16:17], s[0:1], 0x100000
	s_lshl_b32 s33, s15, 10
	s_lshl_b64 s[4:5], s[34:35], 19
	s_lshl_b64 s[16:17], s[16:17], 19
	s_add_u32 s38, s66, s16
	v_lshlrev_b32_e32 v4, 5, v11
	v_bfe_i32 v13, v0, 0, 16
	v_lshlrev_b32_e32 v0, 1, v1
	v_lshrrev_b32_e32 v2, 2, v1
	s_addc_u32 s39, s67, s17
	s_add_i32 s35, s33, 0
	v_and_b32_e32 v4, 32, v4
	v_and_b32_e32 v0, 24, v0
	v_and_b32_e32 v2, 4, v2
	s_add_i32 m0, s35, 0x10000
	v_or3_b32 v0, v3, v2, v0
	v_add_lshl_u32 v2, v4, v13, 1
	global_load_lds_dwordx4 v146, s[38:39]
	s_add_i32 m0, s35, 0x12000
	v_lshl_add_u32 v150, v0, 11, v2
	s_add_u32 s16, s38, 0x40000
	global_load_lds_dwordx4 v150, s[38:39]
	s_addc_u32 s17, s39, 0
	s_add_i32 m0, s35, 0x14000
	v_lshl_add_u32 v148, v1, 11, v2
	global_load_lds_dwordx4 v146, s[16:17]
	s_add_i32 m0, s35, 0x16000
	s_add_u32 s36, s12, s4
	s_addc_u32 s37, s13, s5
	s_add_i32 s42, s35, 0x2000
	global_load_lds_dwordx4 v150, s[16:17]
	s_mov_b32 m0, s35
	s_add_u32 s4, s36, 0x40000
	global_load_lds_dwordx4 v144, s[36:37]
	s_mov_b32 m0, s42
	s_addc_u32 s5, s37, 0
	s_add_i32 s43, s35, 0x4000
	global_load_lds_dwordx4 v148, s[36:37]
	s_mov_b32 m0, s43
	s_add_i32 s44, s35, 0x6000
	global_load_lds_dwordx4 v144, s[4:5]
	s_mov_b32 m0, s44
	v_mov_b32_e32 v147, 0
	global_load_lds_dwordx4 v148, s[4:5]
	v_mov_b32_e32 v151, v147
	v_mov_b32_e32 v145, v147
	v_mov_b32_e32 v149, v147
	s_cmp_eq_u32 s1, 1
	s_mov_b32 s45, 0
	v_lshl_add_u64 v[6:7], s[38:39], 0, v[146:147]
	v_lshl_add_u64 v[4:5], s[38:39], 0, v[150:151]
	v_lshl_add_u64 v[0:1], s[36:37], 0, v[144:145]
	s_cselect_b64 s[4:5], -1, 0
	s_cmp_lg_u32 s1, 1
	v_lshl_add_u64 v[2:3], s[36:37], 0, v[148:149]
	s_cbranch_scc1 .LBB0_986
	s_barrier

; #define PG8_STAGE(bufoff, gbase, voff) do { _Pragma("unroll") for (int _i = 0; _i < 2; ++_i) \
;         __builtin_amdgcn_global_load_lds((const unsigned*)((const char*)(gbase) + (voff)[_i]), (PG8_LAS unsigned*)(lds + (bufoff) + ldsw + _i * 8192), 16, 0, 0); } while (0)
; #define PG8_LDA(dst, b, h) do { _Pragma("unroll") for (int m = 0; m < 4; ++m) _Pragma("unroll") for (int k = 0; k < 2; ++k) dst[m][k] = *(const PG8_LAS bf16x8*)(lds + PG8_SA(b, h) + aoff + m * 2048 + k * 1024); } while (0)
; #define PG8_LDB(dst, b, h) do { _Pragma("unroll") for (int n = 0; n < 2; ++n) _Pragma("unroll") for (int k = 0; k < 2; ++k) dst[n][k] = *(const PG8_LAS bf16x8*)(lds + PG8_SB(b, h) + boff + n * 2048 + k * 1024); } while (0)
; #define PG8_MMA(ai, bj, At, Bt) do { __builtin_amdgcn_s_setprio(1); _Pragma("unroll") for (int m = 0; m < 4; ++m) _Pragma("unroll") for (int n = 0; n < 2; ++n) _Pragma("unroll") for (int k = 0; k < 2; ++k) \
;         acc[ai][bj][m][n] = __builtin_amdgcn_mfma_f32_16x16x32_bf16(Bt[n][k], At[m][k], acc[ai][bj][m][n], 0, 0, 0); __builtin_amdgcn_s_setprio(0); } while (0)
; #define PG8_WAIT_V(n) asm volatile("s_waitcnt vmcnt(" #n ")" ::: "memory")
; #define PG8_BAR __builtin_amdgcn_s_barrier()
; template <class Epi, class Sched, bool ALIGN_EPI = false, bool SP2 = false>
; __device__ __forceinline__ void gemm_phase(PG8_LAS unsigned char* lds, const Gemm g, const Sched& S, const Epi& E) {
;     ...
;         for (int t = 0; t < nt; t += 2) {
;             const bool last = (t == nt - 2);
;             const char* a1 = cA + (size_t)(t + 1) * kstep;
;             const char* a2 = last ? nA : cA + (size_t)(t + 2) * kstep; const char* b2 = last ? nB : cB + (size_t)(t + 2) * kstep;
;             const char* a3 = a2 + kstep; const char* b3 = b2 + kstep;
;             if (last && has_next) S.a_ready(nxt);
;             if constexpr (SP2) {
;             PG8_LDB(B0, 0, 0); PG8_LDB(B1, 0, 1); PG8_SCHED; PG8_LDA(At, 0, 0); PG8_STAGE(PG8_SA(1, 1), a1 + hstep, voffA);
;             PG8_WAIT_V(8); PG8_WAIT_L(0); PG8_BAR; PG8_MMA(0, 0, At, B0); PG8_MMA(0, 1, At, B1); PG8_BAR; PG8_SCHED;
;             PG8_LDA(At, 0, 1); PG8_STAGE(PG8_SB(0, 0), b2, voffB); PG8_STAGE(PG8_SB(0, 1), b2 + hstep, voffB); PG8_STAGE(PG8_SA(0, 0), a2, voffA);
;             PG8_WAIT_V(8); PG8_WAIT_L(0); PG8_BAR; PG8_MMA(1, 0, At, B0); PG8_MMA(1, 1, At, B1); PG8_BAR; PG8_SCHED;
.LBB0_996:
	ds_read_b128 v[128:131], v165
	ds_read_b128 v[132:135], v165 offset:1024
	ds_read_b128 v[136:139], v165 offset:2048
	ds_read_b128 v[140:143], v165 offset:3072
	ds_read_b128 v[168:171], v166
	ds_read_b128 v[172:175], v166 offset:1024
	ds_read_b128 v[176:179], v166 offset:2048
	ds_read_b128 v[180:183], v166 offset:3072
	s_add_u32 s38, s36, 0xfffc0080
	s_addc_u32 s39, s37, -1
	s_cmp_eq_u32 s61, 12
	s_cselect_b32 s41, s27, s39
	s_cselect_b32 s40, s57, s38
	s_cselect_b32 s39, s25, s60
	s_cselect_b32 s38, s58, s59
	v_lshl_add_u64 v[160:161], s[36:37], 0, v[152:153]
	s_add_i32 m0, s35, 0xc000
	ds_read_b128 v[184:187], v167
	ds_read_b128 v[188:191], v167 offset:1024
	ds_read_b128 v[192:195], v167 offset:2048
	ds_read_b128 v[196:199], v167 offset:3072
	ds_read_b128 v[200:203], v167 offset:4096
	ds_read_b128 v[204:207], v167 offset:5120
	ds_read_b128 v[208:211], v167 offset:6144
	ds_read_b128 v[212:215], v167 offset:7168
	global_load_lds_dwordx4 v[160:161], off
	v_lshl_add_u64 v[160:161], s[36:37], 0, v[154:155]
	s_add_i32 m0, s35, 0xe000
	s_nop 0
	global_load_lds_dwordx4 v[160:161], off
	s_waitcnt vmcnt(9)
	s_waitcnt lgkmcnt(0)
	s_barrier
	global_load_dwordx4 v[252:255], v250, s[98:99]
	s_add_u32 s98, s98, 0x1000
	s_addc_u32 s99, s99, 0
	s_setprio 1
	s_waitcnt lgkmcnt(0)
	v_mfma_f32_16x16x32_bf16 v[124:127], v[128:131], v[184:187], v[124:127]
	v_mfma_f32_16x16x32_bf16 v[120:123], v[136:139], v[184:187], v[120:123]
	v_mfma_f32_16x16x32_bf16 v[116:119], v[128:131], v[192:195], v[116:119]
	v_mfma_f32_16x16x32_bf16 v[108:111], v[136:139], v[192:195], v[108:111]
	v_mfma_f32_16x16x32_bf16 v[100:103], v[128:131], v[200:203], v[100:103]
	v_mfma_f32_16x16x32_bf16 v[92:95], v[136:139], v[200:203], v[92:95]
	v_mfma_f32_16x16x32_bf16 v[84:87], v[128:131], v[208:211], v[84:87]
	v_mfma_f32_16x16x32_bf16 v[76:79], v[136:139], v[208:211], v[76:79]
	v_mfma_f32_16x16x32_bf16 v[124:127], v[132:135], v[188:191], v[124:127]
	v_mfma_f32_16x16x32_bf16 v[120:123], v[140:143], v[188:191], v[120:123]
	v_mfma_f32_16x16x32_bf16 v[116:119], v[132:135], v[196:199], v[116:119]
	v_mfma_f32_16x16x32_bf16 v[108:111], v[140:143], v[196:199], v[108:111]
	v_mfma_f32_16x16x32_bf16 v[100:103], v[132:135], v[204:207], v[100:103]
	v_mfma_f32_16x16x32_bf16 v[92:95], v[140:143], v[204:207], v[92:95]
	v_mfma_f32_16x16x32_bf16 v[84:87], v[132:135], v[212:215], v[84:87]
	v_mfma_f32_16x16x32_bf16 v[76:79], v[140:143], v[212:215], v[76:79]
	s_setprio 0
	s_setprio 1
	v_mfma_f32_16x16x32_bf16 v[112:115], v[168:171], v[184:187], v[112:115]
	v_mfma_f32_16x16x32_bf16 v[104:107], v[176:179], v[184:187], v[104:107]
	v_mfma_f32_16x16x32_bf16 v[96:99], v[168:171], v[192:195], v[96:99]
	v_mfma_f32_16x16x32_bf16 v[88:91], v[176:179], v[192:195], v[88:91]
	v_mfma_f32_16x16x32_bf16 v[80:83], v[168:171], v[200:203], v[80:83]
	v_mfma_f32_16x16x32_bf16 v[72:75], v[176:179], v[200:203], v[72:75]
	v_mfma_f32_16x16x32_bf16 v[68:71], v[168:171], v[208:211], v[68:71]
	v_mfma_f32_16x16x32_bf16 v[64:67], v[176:179], v[208:211], v[64:67]
	v_mfma_f32_16x16x32_bf16 v[112:115], v[172:175], v[188:191], v[112:115]
	v_mfma_f32_16x16x32_bf16 v[104:107], v[180:183], v[188:191], v[104:107]
	v_mfma_f32_16x16x32_bf16 v[96:99], v[172:175], v[196:199], v[96:99]
	v_mfma_f32_16x16x32_bf16 v[88:91], v[180:183], v[196:199], v[88:91]
	v_mfma_f32_16x16x32_bf16 v[80:83], v[172:175], v[204:207], v[80:83]
	v_mfma_f32_16x16x32_bf16 v[72:75], v[180:183], v[204:207], v[72:75]
	v_mfma_f32_16x16x32_bf16 v[68:71], v[172:175], v[212:215], v[68:71]
	v_mfma_f32_16x16x32_bf16 v[64:67], v[180:183], v[212:215], v[64:67]
	s_setprio 0
	s_barrier
	s_add_i32 s62, s50, s33
	v_lshl_add_u64 v[160:161], s[38:39], 0, v[146:147]
	s_mov_b32 m0, s62
	ds_read_b128 v[184:187], v167 offset:16384
	ds_read_b128 v[188:191], v167 offset:17408
	ds_read_b128 v[192:195], v167 offset:18432
	ds_read_b128 v[196:199], v167 offset:19456
	ds_read_b128 v[200:203], v167 offset:20480
	ds_read_b128 v[204:207], v167 offset:21504
	ds_read_b128 v[208:211], v167 offset:22528
	ds_read_b128 v[212:215], v167 offset:23552
	global_load_lds_dwordx4 v[160:161], off
	s_add_i32 m0, s62, 0x2000
	s_add_u32 s62, s38, 0x40000
	v_lshl_add_u64 v[216:217], s[38:39], 0, v[150:151]
	s_addc_u32 s63, s39, 0
	s_add_i32 s64, s51, s33
	global_load_lds_dwordx4 v[216:217], off
	v_lshl_add_u64 v[218:219], s[62:63], 0, v[146:147]
	s_mov_b32 m0, s64
	v_lshl_add_u64 v[220:221], s[40:41], 0, v[148:149]
	global_load_lds_dwordx4 v[218:219], off
	v_lshl_add_u64 v[218:219], s[62:63], 0, v[150:151]
	s_add_i32 m0, s64, 0x2000
	s_nop 0
	global_load_lds_dwordx4 v[218:219], off
	v_lshl_add_u64 v[218:219], s[40:41], 0, v[144:145]
	s_mov_b32 m0, s35
	s_nop 0
	global_load_lds_dwordx4 v[218:219], off
	s_mov_b32 m0, s42
	s_nop 0
	global_load_lds_dwordx4 v[220:221], off
	s_waitcnt vmcnt(9)
	s_waitcnt lgkmcnt(0)
	s_barrier
; #define PG8_STAGE(bufoff, gbase, voff) do { _Pragma("unroll") for (int _i = 0; _i < 2; ++_i) \
;         __builtin_amdgcn_global_load_lds((const unsigned*)((const char*)(gbase) + (voff)[_i]), (PG8_LAS unsigned*)(lds + (bufoff) + ldsw + _i * 8192), 16, 0, 0); } while (0)
; #define PG8_LDA(dst, b, h) do { _Pragma("unroll") for (int m = 0; m < 4; ++m) _Pragma("unroll") for (int k = 0; k < 2; ++k) dst[m][k] = *(const PG8_LAS bf16x8*)(lds + PG8_SA(b, h) + aoff + m * 2048 + k * 1024); } while (0)
; #define PG8_LDB(dst, b, h) do { _Pragma("unroll") for (int n = 0; n < 2; ++n) _Pragma("unroll") for (int k = 0; k < 2; ++k) dst[n][k] = *(const PG8_LAS bf16x8*)(lds + PG8_SB(b, h) + boff + n * 2048 + k * 1024); } while (0)
; #define PG8_MMA(ai, bj, At, Bt) do { __builtin_amdgcn_s_setprio(1); _Pragma("unroll") for (int m = 0; m < 4; ++m) _Pragma("unroll") for (int n = 0; n < 2; ++n) _Pragma("unroll") for (int k = 0; k < 2; ++k) \
;         acc[ai][bj][m][n] = __builtin_amdgcn_mfma_f32_16x16x32_bf16(Bt[n][k], At[m][k], acc[ai][bj][m][n], 0, 0, 0); __builtin_amdgcn_s_setprio(0); } while (0)
; #define PG8_WAIT_V(n) asm volatile("s_waitcnt vmcnt(" #n ")" ::: "memory")
; #define PG8_WAIT_L(n) asm volatile("s_waitcnt lgkmcnt(" #n ")" ::: "memory")
; #define PG8_BAR __builtin_amdgcn_s_barrier()
; #define PG8_SCHED __builtin_amdgcn_sched_barrier(0)
; template <class Epi, class Sched, bool ALIGN_EPI = false, bool SP2 = false>
; __device__ __forceinline__ void gemm_phase(PG8_LAS unsigned char* lds, const Gemm g, const Sched& S, const Epi& E) {
;     ...
;             PG8_WAIT_V(8); PG8_WAIT_L(0); PG8_BAR; PG8_MMA(1, 0, At, B0); PG8_MMA(1, 1, At, B1); PG8_BAR; PG8_SCHED;
;             PG8_LDB(B0, 1, 0); PG8_LDB(B1, 1, 1); PG8_SCHED; PG8_LDA(At, 1, 0); PG8_STAGE(PG8_SA(0, 1), a2 + hstep, voffA);
;             PG8_WAIT_V(8); PG8_WAIT_L(0); PG8_BAR; PG8_MMA(0, 0, At, B0); PG8_MMA(0, 1, At, B1); PG8_BAR; PG8_SCHED;
	global_load_dwordx4 v[252:255], v250, s[98:99]
	s_add_u32 s98, s98, 0x1000
	s_addc_u32 s99, s99, 0
	s_setprio 1
	s_waitcnt lgkmcnt(0)
	v_mfma_f32_16x16x32_bf16 v[60:63], v[128:131], v[184:187], v[60:63]
	v_mfma_f32_16x16x32_bf16 v[56:59], v[136:139], v[184:187], v[56:59]
	v_mfma_f32_16x16x32_bf16 v[52:55], v[128:131], v[192:195], v[52:55]
	v_mfma_f32_16x16x32_bf16 v[44:47], v[136:139], v[192:195], v[44:47]
	v_mfma_f32_16x16x32_bf16 v[36:39], v[128:131], v[200:203], v[36:39]
	v_mfma_f32_16x16x32_bf16 v[28:31], v[136:139], v[200:203], v[28:31]
	v_mfma_f32_16x16x32_bf16 v[20:23], v[128:131], v[208:211], v[20:23]
	v_mfma_f32_16x16x32_bf16 v[8:11], v[136:139], v[208:211], v[8:11]
	v_mfma_f32_16x16x32_bf16 v[60:63], v[132:135], v[188:191], v[60:63]
	v_mfma_f32_16x16x32_bf16 v[56:59], v[140:143], v[188:191], v[56:59]
	v_mfma_f32_16x16x32_bf16 v[52:55], v[132:135], v[196:199], v[52:55]
	v_mfma_f32_16x16x32_bf16 v[44:47], v[140:143], v[196:199], v[44:47]
	v_mfma_f32_16x16x32_bf16 v[36:39], v[132:135], v[204:207], v[36:39]
	v_mfma_f32_16x16x32_bf16 v[28:31], v[140:143], v[204:207], v[28:31]
	v_mfma_f32_16x16x32_bf16 v[20:23], v[132:135], v[212:215], v[20:23]
	v_mfma_f32_16x16x32_bf16 v[8:11], v[140:143], v[212:215], v[8:11]
	s_setprio 0
	s_setprio 1
	v_mfma_f32_16x16x32_bf16 v[48:51], v[168:171], v[184:187], v[48:51]
	v_mfma_f32_16x16x32_bf16 v[40:43], v[176:179], v[184:187], v[40:43]
	v_mfma_f32_16x16x32_bf16 v[32:35], v[168:171], v[192:195], v[32:35]
	v_mfma_f32_16x16x32_bf16 v[24:27], v[176:179], v[192:195], v[24:27]
	v_mfma_f32_16x16x32_bf16 v[16:19], v[168:171], v[200:203], v[16:19]
	v_mfma_f32_16x16x32_bf16 v[12:15], v[176:179], v[200:203], v[12:15]
	v_mfma_f32_16x16x32_bf16 v[4:7], v[168:171], v[208:211], v[4:7]
	v_mfma_f32_16x16x32_bf16 v[0:3], v[176:179], v[208:211], v[0:3]
	v_mfma_f32_16x16x32_bf16 v[48:51], v[172:175], v[188:191], v[48:51]
	v_mfma_f32_16x16x32_bf16 v[40:43], v[180:183], v[188:191], v[40:43]
	v_mfma_f32_16x16x32_bf16 v[32:35], v[172:175], v[196:199], v[32:35]
	v_mfma_f32_16x16x32_bf16 v[24:27], v[180:183], v[196:199], v[24:27]
	v_mfma_f32_16x16x32_bf16 v[16:19], v[172:175], v[204:207], v[16:19]
	v_mfma_f32_16x16x32_bf16 v[12:15], v[180:183], v[204:207], v[12:15]
	v_mfma_f32_16x16x32_bf16 v[4:7], v[172:175], v[212:215], v[4:7]
	v_mfma_f32_16x16x32_bf16 v[0:3], v[180:183], v[212:215], v[0:3]
	s_setprio 0
	s_barrier
	s_add_i32 s62, 0, 0x18000
	s_add_i32 s63, 0, 0x1c000
	v_add_u32_e32 v140, s62, v163
	v_add_u32_e32 v180, s63, v163
	ds_read_b128 v[128:131], v140
	ds_read_b128 v[132:135], v140 offset:1024
	ds_read_b128 v[136:139], v140 offset:2048
	ds_read_b128 v[140:143], v140 offset:3072
	ds_read_b128 v[168:171], v180
	ds_read_b128 v[172:175], v180 offset:1024
	ds_read_b128 v[176:179], v180 offset:2048
	ds_read_b128 v[180:183], v180 offset:3072
	s_add_u32 s40, s40, 0x40000
	s_addc_u32 s41, s41, 0
	s_mov_b32 m0, s43
	v_lshl_add_u64 v[222:223], s[40:41], 0, v[144:145]
	ds_read_b128 v[184:187], v167 offset:32768
	ds_read_b128 v[188:191], v167 offset:33792
	ds_read_b128 v[192:195], v167 offset:34816
	ds_read_b128 v[196:199], v167 offset:35840
	ds_read_b128 v[200:203], v167 offset:36864
	ds_read_b128 v[204:207], v167 offset:37888
	ds_read_b128 v[208:211], v167 offset:38912
	ds_read_b128 v[212:215], v167 offset:39936
	global_load_lds_dwordx4 v[222:223], off
	v_lshl_add_u64 v[222:223], s[40:41], 0, v[148:149]
	s_mov_b32 m0, s44
	s_nop 0
	global_load_lds_dwordx4 v[222:223], off
	s_waitcnt vmcnt(9)
	s_waitcnt lgkmcnt(0)
	s_barrier
	global_load_dwordx4 v[252:255], v250, s[98:99]
	s_add_u32 s98, s98, 0x1000
	s_addc_u32 s99, s99, 0
	s_setprio 1
	s_waitcnt lgkmcnt(0)
	v_mfma_f32_16x16x32_bf16 v[124:127], v[128:131], v[184:187], v[124:127]
	v_mfma_f32_16x16x32_bf16 v[120:123], v[136:139], v[184:187], v[120:123]
	v_mfma_f32_16x16x32_bf16 v[116:119], v[128:131], v[192:195], v[116:119]
	v_mfma_f32_16x16x32_bf16 v[108:111], v[136:139], v[192:195], v[108:111]
	v_mfma_f32_16x16x32_bf16 v[100:103], v[128:131], v[200:203], v[100:103]
	v_mfma_f32_16x16x32_bf16 v[92:95], v[136:139], v[200:203], v[92:95]
	v_mfma_f32_16x16x32_bf16 v[84:87], v[128:131], v[208:211], v[84:87]
	v_mfma_f32_16x16x32_bf16 v[76:79], v[136:139], v[208:211], v[76:79]
	v_mfma_f32_16x16x32_bf16 v[124:127], v[132:135], v[188:191], v[124:127]
	v_mfma_f32_16x16x32_bf16 v[120:123], v[140:143], v[188:191], v[120:123]
	v_mfma_f32_16x16x32_bf16 v[116:119], v[132:135], v[196:199], v[116:119]
	v_mfma_f32_16x16x32_bf16 v[108:111], v[140:143], v[196:199], v[108:111]
	v_mfma_f32_16x16x32_bf16 v[100:103], v[132:135], v[204:207], v[100:103]
	v_mfma_f32_16x16x32_bf16 v[92:95], v[140:143], v[204:207], v[92:95]
	v_mfma_f32_16x16x32_bf16 v[84:87], v[132:135], v[212:215], v[84:87]
	v_mfma_f32_16x16x32_bf16 v[76:79], v[140:143], v[212:215], v[76:79]
	s_setprio 0
	s_setprio 1
	v_mfma_f32_16x16x32_bf16 v[112:115], v[168:171], v[184:187], v[112:115]
	v_mfma_f32_16x16x32_bf16 v[104:107], v[176:179], v[184:187], v[104:107]
	v_mfma_f32_16x16x32_bf16 v[96:99], v[168:171], v[192:195], v[96:99]
	v_mfma_f32_16x16x32_bf16 v[88:91], v[176:179], v[192:195], v[88:91]
	v_mfma_f32_16x16x32_bf16 v[80:83], v[168:171], v[200:203], v[80:83]
	v_mfma_f32_16x16x32_bf16 v[72:75], v[176:179], v[200:203], v[72:75]
	v_mfma_f32_16x16x32_bf16 v[68:71], v[168:171], v[208:211], v[68:71]
	v_mfma_f32_16x16x32_bf16 v[64:67], v[176:179], v[208:211], v[64:67]
	v_mfma_f32_16x16x32_bf16 v[112:115], v[172:175], v[188:191], v[112:115]
	v_mfma_f32_16x16x32_bf16 v[104:107], v[180:183], v[188:191], v[104:107]
	v_mfma_f32_16x16x32_bf16 v[96:99], v[172:175], v[196:199], v[96:99]
	v_mfma_f32_16x16x32_bf16 v[88:91], v[180:183], v[196:199], v[88:91]
	v_mfma_f32_16x16x32_bf16 v[80:83], v[172:175], v[204:207], v[80:83]
	v_mfma_f32_16x16x32_bf16 v[72:75], v[180:183], v[204:207], v[72:75]
	v_mfma_f32_16x16x32_bf16 v[68:71], v[172:175], v[212:215], v[68:71]
	v_mfma_f32_16x16x32_bf16 v[64:67], v[180:183], v[212:215], v[64:67]
	s_setprio 0
	s_barrier
; #define PG8_STAGE(bufoff, gbase, voff) do { _Pragma("unroll") for (int _i = 0; _i < 2; ++_i) \
;         __builtin_amdgcn_global_load_lds((const unsigned*)((const char*)(gbase) + (voff)[_i]), (PG8_LAS unsigned*)(lds + (bufoff) + ldsw + _i * 8192), 16, 0, 0); } while (0)
; #define PG8_LDA(dst, b, h) do { _Pragma("unroll") for (int m = 0; m < 4; ++m) _Pragma("unroll") for (int k = 0; k < 2; ++k) dst[m][k] = *(const PG8_LAS bf16x8*)(lds + PG8_SA(b, h) + aoff + m * 2048 + k * 1024); } while (0)
; #define PG8_LDB(dst, b, h) do { _Pragma("unroll") for (int n = 0; n < 2; ++n) _Pragma("unroll") for (int k = 0; k < 2; ++k) dst[n][k] = *(const PG8_LAS bf16x8*)(lds + PG8_SB(b, h) + boff + n * 2048 + k * 1024); } while (0)
; template <class Epi, class Sched, bool ALIGN_EPI = false, bool SP2 = false>
; __device__ __forceinline__ void gemm_phase(PG8_LAS unsigned char* lds, const Gemm g, const Sched& S, const Epi& E) {
;     ...
;         for (int t = 0; t < nt; t += 2) {
;             const bool last = (t == nt - 2);
;             const char* a1 = cA + (size_t)(t + 1) * kstep;
;             const char* a2 = last ? nA : cA + (size_t)(t + 2) * kstep; const char* b2 = last ? nB : cB + (size_t)(t + 2) * kstep;
;             const char* a3 = a2 + kstep; const char* b3 = b2 + kstep;
;             if (last && has_next) S.a_ready(nxt);
;             if constexpr (SP2) {
;             PG8_LDB(B0, 0, 0); PG8_LDB(B1, 0, 1); PG8_SCHED; PG8_LDA(At, 0, 0); PG8_STAGE(PG8_SA(1, 1), a1 + hstep, voffA);
;             PG8_WAIT_V(8); PG8_WAIT_L(0); PG8_BAR; PG8_MMA(0, 0, At, B0); PG8_MMA(0, 1, At, B1); PG8_BAR; PG8_SCHED;
;             PG8_LDA(At, 0, 1); PG8_STAGE(PG8_SB(0, 0), b2, voffB); PG8_STAGE(PG8_SB(0, 1), b2 + hstep, voffB); PG8_STAGE(PG8_SA(0, 0), a2, voffA);
;             PG8_WAIT_V(8); PG8_WAIT_L(0); PG8_BAR; PG8_MMA(1, 0, At, B0); PG8_MMA(1, 1, At, B1); PG8_BAR; PG8_SCHED;
;             PG8_LDB(B0, 1, 0); PG8_LDB(B1, 1, 1); PG8_SCHED; PG8_LDA(At, 1, 0); PG8_STAGE(PG8_SA(0, 1), a2 + hstep, voffA);
;             PG8_WAIT_V(8); PG8_WAIT_L(0); PG8_BAR; PG8_MMA(0, 0, At, B0); PG8_MMA(0, 1, At, B1); PG8_BAR; PG8_SCHED;
;             PG8_LDA(At, 1, 1); PG8_STAGE(PG8_SB(1, 0), b3, voffB); PG8_STAGE(PG8_SB(1, 1), b3 + hstep, voffB); PG8_STAGE(PG8_SA(1, 0), a3, voffA);
;             PG8_WAIT_V(8); PG8_WAIT_L(0); PG8_BAR; PG8_MMA(1, 0, At, B0); PG8_MMA(1, 1, At, B1); PG8_BAR; PG8_SCHED;
	s_add_i32 s40, s62, s33
	v_lshl_add_u64 v[160:161], v[160:161], 0, s[10:11]
	s_mov_b32 m0, s40
	ds_read_b128 v[184:187], v167 offset:49152
	ds_read_b128 v[188:191], v167 offset:50176
	ds_read_b128 v[192:195], v167 offset:51200
	ds_read_b128 v[196:199], v167 offset:52224
	ds_read_b128 v[200:203], v167 offset:53248
	ds_read_b128 v[204:207], v167 offset:54272
	ds_read_b128 v[208:211], v167 offset:55296
	ds_read_b128 v[212:215], v167 offset:56320
	global_load_lds_dwordx4 v[160:161], off
	s_add_i32 m0, s40, 0x2000
	s_add_u32 s38, s38, 0x40080
	v_lshl_add_u64 v[160:161], v[216:217], 0, s[10:11]
	s_addc_u32 s39, s39, 0
	s_add_i32 s40, s63, s33
	global_load_lds_dwordx4 v[160:161], off
	v_lshl_add_u64 v[160:161], s[38:39], 0, v[146:147]
	s_mov_b32 m0, s40
	s_nop 0
	global_load_lds_dwordx4 v[160:161], off
	v_lshl_add_u64 v[160:161], s[38:39], 0, v[150:151]
	s_add_i32 m0, s40, 0x2000
	s_nop 0
	global_load_lds_dwordx4 v[160:161], off
	v_lshl_add_u64 v[160:161], v[218:219], 0, s[10:11]
	s_mov_b32 m0, s48
	s_nop 0
	global_load_lds_dwordx4 v[160:161], off
	v_lshl_add_u64 v[160:161], v[220:221], 0, s[10:11]
	s_mov_b32 m0, s49
	s_nop 0
	global_load_lds_dwordx4 v[160:161], off
	s_waitcnt vmcnt(9)
	s_waitcnt lgkmcnt(0)
	s_barrier
	global_load_dwordx4 v[252:255], v250, s[98:99]
	s_add_u32 s98, s98, 0x1000
	s_addc_u32 s99, s99, 0
	s_setprio 1
	s_waitcnt lgkmcnt(0)
	v_mfma_f32_16x16x32_bf16 v[60:63], v[128:131], v[184:187], v[60:63]
	v_mfma_f32_16x16x32_bf16 v[56:59], v[136:139], v[184:187], v[56:59]
	v_mfma_f32_16x16x32_bf16 v[52:55], v[128:131], v[192:195], v[52:55]
	v_mfma_f32_16x16x32_bf16 v[44:47], v[136:139], v[192:195], v[44:47]
	v_mfma_f32_16x16x32_bf16 v[36:39], v[128:131], v[200:203], v[36:39]
	v_mfma_f32_16x16x32_bf16 v[28:31], v[136:139], v[200:203], v[28:31]
	v_mfma_f32_16x16x32_bf16 v[20:23], v[128:131], v[208:211], v[20:23]
	v_mfma_f32_16x16x32_bf16 v[8:11], v[136:139], v[208:211], v[8:11]
	v_mfma_f32_16x16x32_bf16 v[60:63], v[132:135], v[188:191], v[60:63]
	v_mfma_f32_16x16x32_bf16 v[56:59], v[140:143], v[188:191], v[56:59]
	v_mfma_f32_16x16x32_bf16 v[52:55], v[132:135], v[196:199], v[52:55]
	v_mfma_f32_16x16x32_bf16 v[44:47], v[140:143], v[196:199], v[44:47]
	v_mfma_f32_16x16x32_bf16 v[36:39], v[132:135], v[204:207], v[36:39]
	v_mfma_f32_16x16x32_bf16 v[28:31], v[140:143], v[204:207], v[28:31]
	v_mfma_f32_16x16x32_bf16 v[20:23], v[132:135], v[212:215], v[20:23]
	v_mfma_f32_16x16x32_bf16 v[8:11], v[140:143], v[212:215], v[8:11]
	s_setprio 0
	s_setprio 1
	v_mfma_f32_16x16x32_bf16 v[48:51], v[168:171], v[184:187], v[48:51]
	v_mfma_f32_16x16x32_bf16 v[40:43], v[176:179], v[184:187], v[40:43]
	v_mfma_f32_16x16x32_bf16 v[32:35], v[168:171], v[192:195], v[32:35]
	v_mfma_f32_16x16x32_bf16 v[24:27], v[176:179], v[192:195], v[24:27]
	v_mfma_f32_16x16x32_bf16 v[16:19], v[168:171], v[200:203], v[16:19]
	v_mfma_f32_16x16x32_bf16 v[12:15], v[176:179], v[200:203], v[12:15]
	v_mfma_f32_16x16x32_bf16 v[4:7], v[168:171], v[208:211], v[4:7]
	v_mfma_f32_16x16x32_bf16 v[0:3], v[176:179], v[208:211], v[0:3]
	v_mfma_f32_16x16x32_bf16 v[48:51], v[172:175], v[188:191], v[48:51]
	v_mfma_f32_16x16x32_bf16 v[40:43], v[180:183], v[188:191], v[40:43]
	v_mfma_f32_16x16x32_bf16 v[32:35], v[172:175], v[196:199], v[32:35]
	v_mfma_f32_16x16x32_bf16 v[24:27], v[180:183], v[196:199], v[24:27]
	v_mfma_f32_16x16x32_bf16 v[16:19], v[172:175], v[204:207], v[16:19]
	v_mfma_f32_16x16x32_bf16 v[12:15], v[180:183], v[204:207], v[12:15]
	v_mfma_f32_16x16x32_bf16 v[4:7], v[172:175], v[212:215], v[4:7]
	v_mfma_f32_16x16x32_bf16 v[0:3], v[180:183], v[212:215], v[0:3]
	s_setprio 0
	s_barrier
	s_add_i32 s61, s61, 2
	s_add_u32 s36, s36, 0x100
	s_addc_u32 s37, s37, 0
	s_add_u32 s59, s59, 0x100
	s_addc_u32 s60, s60, 0
	s_cmp_gt_u32 s61, 13
	s_cbranch_scc0 .LBB0_996
	s_and_b64 vcc, exec, s[14:15]
	s_cbranch_vccz .LBB0_999
	s_barrier

; __global__ void __launch_bounds__(NTHR, 2) fwd_megakernel(Args args) {
	.amdhsa_kernel _Z14fwd_megakernel4Args
		.amdhsa_group_segment_fixed_size 0
		.amdhsa_private_segment_fixed_size 0
		.amdhsa_kernarg_size 400
		.amdhsa_user_sgpr_count 2
		.amdhsa_user_sgpr_dispatch_ptr 0
		.amdhsa_user_sgpr_queue_ptr 0
		.amdhsa_user_sgpr_kernarg_segment_ptr 1
		.amdhsa_user_sgpr_dispatch_id 0
		.amdhsa_user_sgpr_kernarg_preload_length 0
		.amdhsa_user_sgpr_kernarg_preload_offset 0
		.amdhsa_user_sgpr_private_segment_size 0
		.amdhsa_uses_dynamic_stack 0
		.amdhsa_enable_private_segment 0
		.amdhsa_system_sgpr_workgroup_id_x 1
		.amdhsa_system_sgpr_workgroup_id_y 0
		.amdhsa_system_sgpr_workgroup_id_z 0
		.amdhsa_system_sgpr_workgroup_info 0
		.amdhsa_system_vgpr_workitem_id 2
		.amdhsa_next_free_vgpr 256
		.amdhsa_next_free_sgpr 102
		.amdhsa_accum_offset 256
		.amdhsa_reserve_vcc 1
		.amdhsa_float_round_mode_32 0
		.amdhsa_float_round_mode_16_64 0
		.amdhsa_float_denorm_mode_32 3
		.amdhsa_float_denorm_mode_16_64 3
		.amdhsa_dx10_clamp 1
		.amdhsa_ieee_mode 1
		.amdhsa_fp16_overflow 0
		.amdhsa_tg_split 0
		.amdhsa_exception_fp_ieee_invalid_op 0
		.amdhsa_exception_fp_denorm_src 0
		.amdhsa_exception_fp_ieee_div_zero 0
		.amdhsa_exception_fp_ieee_overflow 0
		.amdhsa_exception_fp_ieee_underflow 0
		.amdhsa_exception_fp_ieee_inexact 0
		.amdhsa_exception_int_div_zero 0
	.end_amdhsa_kernel

; __global__ void __launch_bounds__(NTHR, 2) fwd_megakernel(Args args) {
amdhsa.kernels:
  - .agpr_count:     0
    .args:
      - .offset:         0
        .size:           144
        .value_kind:     by_value
      - .offset:         144
        .size:           4
        .value_kind:     hidden_block_count_x
      - .offset:         148
        .size:           4
        .value_kind:     hidden_block_count_y
      - .offset:         152
        .size:           4
        .value_kind:     hidden_block_count_z
      - .offset:         156
        .size:           2
        .value_kind:     hidden_group_size_x
      - .offset:         158
        .size:           2
        .value_kind:     hidden_group_size_y
      - .offset:         160
        .size:           2
        .value_kind:     hidden_group_size_z
      - .offset:         162
        .size:           2
        .value_kind:     hidden_remainder_x
      - .offset:         164
        .size:           2
        .value_kind:     hidden_remainder_y
      - .offset:         166
        .size:           2
        .value_kind:     hidden_remainder_z
      - .offset:         184
        .size:           8
        .value_kind:     hidden_global_offset_x
      - .offset:         192
        .size:           8
        .value_kind:     hidden_global_offset_y
      - .offset:         200
        .size:           8
        .value_kind:     hidden_global_offset_z
      - .offset:         208
        .size:           2
        .value_kind:     hidden_grid_dims
      - .offset:         232
        .size:           8
        .value_kind:     hidden_multigrid_sync_arg
      - .offset:         264
        .size:           4
        .value_kind:     hidden_dynamic_lds_size
    .group_segment_fixed_size: 0
    .kernarg_segment_align: 8
    .kernarg_segment_size: 400
    .language:       OpenCL C
    .language_version:
      - 2
      - 0
    .max_flat_workgroup_size: 512
    .name:           _Z14fwd_megakernel4Args
    .private_segment_fixed_size: 0
    .sgpr_count:     108
    .sgpr_spill_count: 79
    .symbol:         _Z14fwd_megakernel4Args.kd
    .uniform_work_group_size: 1
    .uses_dynamic_stack: false
    .vgpr_count:     256
    .vgpr_spill_count: 0
    .wavefront_size: 64
